# chunk_scan step: third staging piece unconditional (dummy LDS slot for lanes without one, no exec save/restore), packed f32 multiplies replaced by scalar multiplies
# speedup vs baseline: 1.0223x; 1.0004x over previous
.LBB0_901:
	s_andn2_saveexec_b64 s[12:13], s[12:13]
	v_lshlrev_b32_e32 v1, 4, v0
	v_and_b32_e32 v2, 0xffffff80, v1
	v_xor_b32_e32 v0, v1, v0
	s_movk_i32 s34, 0x70
	v_and_or_b32 v189, v0, s34, v2
	s_or_b64 exec, exec, s[12:13]
	v_lshlrev_b32_e32 v251, 4, v178
	v_add_u32_e32 v251, 0x8000, v251
	v_mov_b32_e32 v252, 0xaf
	v_cmp_lt_u32_e64 s[12:13], v252, v178
	s_nop 1
	v_cndmask_b32_e64 v189, v189, v251, s[12:13]
	v_ashrrev_i32_e32 v52, 3, v104
	v_lshlrev_b32_e32 v0, 8, v104
	v_readlane_b32 s12, v236, 42
	v_lshlrev_b32_e32 v105, 11, v52
	v_and_b32_e32 v106, 0x700, v0
	v_readlane_b32 s13, v236, 43
	v_or_b32_e32 v2, v106, v105
	v_ashrrev_i32_e32 v103, 31, v102
	v_mov_b64_e32 v[0:1], s[12:13]
	s_movk_i32 s12, 0x2b00
	v_mad_i64_i32 v[0:1], s[12:13], v2, s12, v[0:1]
	v_lshl_add_u64 v[54:55], v[0:1], 0, v[102:103]
	s_setprio 3
	v_add_co_u32_e32 v0, vcc, 0x1000, v54
	v_mov_b32_e32 v2, v3
	s_nop 0
	v_addc_co_u32_e32 v1, vcc, 0, v55, vcc
	global_load_dwordx4 v[44:47], v[54:55], off
	global_load_dwordx4 v[48:51], v[0:1], off
	v_mov_b32_e32 v0, v3
	v_mov_b32_e32 v1, v3
	v_mov_b64_e32 v[6:7], v[2:3]
	v_mov_b64_e32 v[4:5], v[0:1]
	s_and_saveexec_b64 s[12:13], s[42:43]
	s_cbranch_execz .LBB0_905
	v_add_co_u32_e32 v4, vcc, 0x2000, v54
	s_nop 1
	v_addc_co_u32_e32 v5, vcc, 0, v55, vcc
	global_load_dwordx4 v[4:7], v[4:5], off

.LBB0_916:
	v_cvt_pk_bf16_f32 v210, v142, v143
	v_cvt_pk_bf16_f32 v211, v144, v145
	v_cvt_pk_bf16_f32 v212, v146, v147
	v_cvt_pk_bf16_f32 v213, v148, v149
	v_cvt_pk_bf16_f32 v218, v154, v155
	v_cvt_pk_bf16_f32 v219, v156, v157
	s_nop 0
	v_lshlrev_b32_e32 v0, 16, v210
	v_and_b32_e32 v1, 0xffff0000, v210
	v_sub_f32_e32 v0, v142, v0
	v_sub_f32_e32 v1, v143, v1
	v_cvt_pk_bf16_f32 v214, v0, v1
	v_lshlrev_b32_e32 v0, 16, v211
	v_and_b32_e32 v1, 0xffff0000, v211
	v_sub_f32_e32 v0, v144, v0
	v_sub_f32_e32 v1, v145, v1
	v_mfma_f32_16x16x32_bf16 v[224:227], v[170:173], v[210:213], 0
	v_cvt_pk_bf16_f32 v215, v0, v1
	v_lshlrev_b32_e32 v0, 16, v212
	v_and_b32_e32 v1, 0xffff0000, v212
	v_sub_f32_e32 v0, v146, v0
	v_sub_f32_e32 v1, v147, v1
	v_cvt_pk_bf16_f32 v216, v0, v1
	v_lshlrev_b32_e32 v0, 16, v213
	v_and_b32_e32 v1, 0xffff0000, v213
	v_sub_f32_e32 v0, v148, v0
	v_sub_f32_e32 v1, v149, v1
	v_cvt_pk_bf16_f32 v217, v0, v1
	v_lshlrev_b32_e32 v0, 16, v218
	v_mfma_f32_16x16x32_bf16 v[170:173], v[170:173], v[214:217], v[224:227]
	v_and_b32_e32 v1, 0xffff0000, v218
	v_sub_f32_e32 v0, v154, v0
	v_sub_f32_e32 v1, v155, v1
	v_cvt_pk_bf16_f32 v222, v0, v1
	v_lshlrev_b32_e32 v0, 16, v219
	v_and_b32_e32 v1, 0xffff0000, v219
	v_cvt_pk_bf16_f32 v220, v158, v159
	v_cvt_pk_bf16_f32 v221, v160, v161
	v_sub_f32_e32 v0, v156, v0
	v_sub_f32_e32 v1, v157, v1
	v_mfma_f32_16x16x32_bf16 v[170:173], v[162:165], v[218:221], v[170:173]
	v_cvt_pk_bf16_f32 v223, v0, v1
	v_lshlrev_b32_e32 v0, 16, v220
	v_and_b32_e32 v1, 0xffff0000, v220
	v_sub_f32_e32 v0, v158, v0
	v_sub_f32_e32 v1, v159, v1
	v_cvt_pk_bf16_f32 v224, v0, v1
	v_lshlrev_b32_e32 v0, 16, v221
	v_and_b32_e32 v1, 0xffff0000, v221
	v_mov_b32_e32 v152, v3
	v_mov_b32_e32 v153, v3
	v_sub_f32_e32 v0, v160, v0
	v_sub_f32_e32 v1, v161, v1
	v_cvt_pk_bf16_f32 v225, v0, v1
	v_mov_b32_e32 v176, v3
	v_mfma_f32_16x16x32_bf16 v[162:165], v[162:165], v[222:225], v[170:173]
	v_mov_b32_e32 v177, v3
	v_mul_f32_e32 v144, v168, v144
	v_mul_f32_e32 v145, v169, v145
	v_mul_f32_e32 v142, v166, v142
	v_mul_f32_e32 v143, v167, v143
	v_mfma_f32_16x16x32_bf16 v[150:153], v[150:153], v[174:177], v[162:165]
	v_mfma_f32_16x16x32_bf16 v[162:165], v[118:121], v[210:213], 0
	s_nop 0
	v_mfma_f32_16x16x32_bf16 v[118:121], v[118:121], v[214:217], v[162:165]
	s_add_i32 s34, s34, 4
	v_mfma_f32_16x16x32_bf16 v[118:121], v[134:137], v[218:221], v[118:121]
	v_mfma_f32_16x16x32_bf16 v[118:121], v[134:137], v[222:225], v[118:121]
	v_mov_b32_e32 v136, v174
	v_mov_b32_e32 v137, v175
	s_nop 5
	v_cvt_pk_bf16_f32 v134, -v118, -v119
	v_cvt_pk_bf16_f32 v135, -v120, -v121
	v_lshlrev_b32_e32 v0, 16, v134
	v_and_b32_e32 v1, 0xffff0000, v134
	v_sub_f32_e64 v0, -v118, v0
	v_sub_f32_e64 v1, -v119, v1
	v_mfma_f32_16x16x32_bf16 v[142:145], v[114:117], v[134:137], v[142:145]
	v_cvt_pk_bf16_f32 v0, v0, v1
	v_lshlrev_b32_e32 v1, 16, v135
	v_and_b32_e32 v2, 0xffff0000, v135
	v_sub_f32_e64 v1, -v120, v1
	v_sub_f32_e64 v2, -v121, v2
	v_cvt_pk_bf16_f32 v1, v1, v2
	v_mov_b32_e32 v2, v3
	s_nop 1
	v_mfma_f32_16x16x32_bf16 v[118:121], v[114:117], v[0:3], v[142:145]
	v_mul_f32_e64 v116, v140, v148
	v_mul_f32_e64 v117, v141, v149
	v_mul_f32_e32 v114, v138, v146
	v_mul_f32_e32 v115, v139, v147
	s_nop 1
	v_mfma_f32_16x16x32_bf16 v[114:117], v[110:113], v[134:137], v[114:117]
	v_mfma_f32_16x16x32_bf16 v[114:117], v[110:113], v[0:3], v[114:117]
	v_mul_f32_e64 v112, v132, v156
	v_mul_f32_e64 v113, v133, v157
	v_mul_f32_e32 v110, v130, v154
	v_mul_f32_e32 v111, v131, v155
	s_nop 0
	s_nop 0
	v_mfma_f32_16x16x32_bf16 v[110:113], v[106:109], v[134:137], v[110:113]
	s_mov_b64 s[12:13], 0xac00
	v_mfma_f32_16x16x32_bf16 v[110:113], v[106:109], v[0:3], v[110:113]
	v_mul_f32_e64 v108, v128, v160
	v_mul_f32_e64 v109, v129, v161
	v_mul_f32_e32 v106, v126, v158
	v_mul_f32_e32 v107, v127, v159
	v_lshl_add_u64 v[182:183], v[182:183], 0, s[12:13]
	s_mov_b64 s[12:13], 0x20000
	v_mfma_f32_16x16x32_bf16 v[106:109], v[122:125], v[134:137], v[106:109]
	v_lshl_add_u64 v[184:185], v[184:185], 0, s[12:13]
	s_andn2_b64 vcc, exec, s[40:41]
	global_store_dword v250, v150, s[24:25] offset:-4096
	v_mfma_f32_16x16x32_bf16 v[106:109], v[122:125], v[0:3], v[106:109]
	s_waitcnt lgkmcnt(9)
	v_mov_b64_e32 v[0:1], v[104:105]
	global_store_dword v250, v151, s[24:25] offset:-2048
	global_store_dword v250, v152, s[24:25]
	global_store_dword v250, v153, s[24:25] offset:2048
	v_add_u32_e32 v250, 0x8000, v250
	s_cbranch_vccz .LBB0_656
.LBB0_917:
	s_waitcnt vmcnt(21)
	ds_write_b128 v181, v[8:11] offset:11008
	s_waitcnt vmcnt(20)
	ds_write_b128 v188, v[12:15] offset:11008
	ds_write_b128 v189, v[16:19] offset:11008
	s_cmpk_gt_u32 s34, 0xfa
	s_cbranch_scc1 .LBB0_923
	global_load_dwordx4 v[8:11], v248, s[100:101] offset:-4096
	s_nop 0
	global_load_dwordx4 v[12:15], v248, s[100:101]
	global_load_dwordx4 v[16:19], v249, s[100:101]
.LBB0_922:
	s_add_u32 s100, s100, 0x2b00
	s_addc_u32 s101, s101, 0
.LBB0_923:
	v_cvt_pk_bf16_f32 v122, v118, v119
	v_cvt_pk_bf16_f32 v123, v120, v121
	v_cvt_pk_bf16_f32 v124, v114, v115
	v_cvt_pk_bf16_f32 v125, v116, v117
	v_cvt_pk_bf16_f32 v130, v110, v111
	v_cvt_pk_bf16_f32 v131, v112, v113
	s_nop 0
	v_and_b32_e32 v102, 0xffff0000, v122
	v_lshlrev_b32_e32 v2, 16, v122
	v_sub_f32_e32 v102, v119, v102
	v_sub_f32_e32 v2, v118, v2
	v_cvt_pk_bf16_f32 v126, v2, v102
	v_and_b32_e32 v102, 0xffff0000, v123
	v_lshlrev_b32_e32 v2, 16, v123
	v_sub_f32_e32 v102, v121, v102
	v_sub_f32_e32 v2, v120, v2
	v_cvt_pk_bf16_f32 v127, v2, v102
	v_and_b32_e32 v102, 0xffff0000, v124
	v_lshlrev_b32_e32 v2, 16, v124
	v_sub_f32_e32 v102, v115, v102
	v_sub_f32_e32 v2, v114, v2
	v_cvt_pk_bf16_f32 v128, v2, v102
	v_and_b32_e32 v102, 0xffff0000, v125
	v_lshlrev_b32_e32 v2, 16, v125
	v_sub_f32_e32 v102, v117, v102
	v_sub_f32_e32 v2, v116, v2
	v_cvt_pk_bf16_f32 v129, v2, v102
	v_and_b32_e32 v102, 0xffff0000, v130
	v_lshlrev_b32_e32 v2, 16, v130
	v_sub_f32_e32 v102, v111, v102
	v_sub_f32_e32 v2, v110, v2
	v_cvt_pk_bf16_f32 v146, v2, v102
	v_and_b32_e32 v102, 0xffff0000, v131
	v_lshlrev_b32_e32 v2, 16, v131
	v_sub_f32_e32 v102, v113, v102
	v_sub_f32_e32 v2, v112, v2
	v_cvt_pk_bf16_f32 v147, v2, v102
	s_waitcnt lgkmcnt(14)
	v_mfma_f32_16x16x32_bf16 v[102:105], v[92:95], v[122:125], 0
	v_cvt_pk_bf16_f32 v132, v106, v107
	v_cvt_pk_bf16_f32 v133, v108, v109
	s_waitcnt lgkmcnt(3)
	v_mov_b32_e32 v160, v100
	v_mfma_f32_16x16x32_bf16 v[92:95], v[92:95], v[126:129], v[102:105]
	v_lshlrev_b32_e32 v2, 16, v132
	v_sub_f32_e32 v2, v106, v2
	v_and_b32_e32 v134, 0xffff0000, v132
	v_mfma_f32_16x16x32_bf16 v[92:95], v[88:91], v[130:133], v[92:95]
	v_sub_f32_e32 v134, v107, v134
	v_cvt_pk_bf16_f32 v148, v2, v134
	v_lshlrev_b32_e32 v2, 16, v133
	v_sub_f32_e32 v2, v108, v2
	v_and_b32_e32 v102, 0xffff0000, v133
	v_sub_f32_e32 v102, v109, v102
	v_cvt_pk_bf16_f32 v149, v2, v102
	v_mov_b32_e32 v2, v3
	v_mfma_f32_16x16x32_bf16 v[88:91], v[88:91], v[146:149], v[92:95]
	v_mov_b32_e32 v102, v3
	v_mov_b32_e32 v103, v3
	v_mov_b32_e32 v161, v101
	v_mfma_f32_16x16x32_bf16 v[92:95], v[76:79], v[122:125], 0
	v_mul_f32_e64 v98, v120, v98
	v_mul_f32_e64 v99, v121, v99
	v_mul_f32_e32 v96, v118, v96
	v_mul_f32_e32 v97, v119, v97
	s_waitcnt lgkmcnt(0)
	v_mfma_f32_16x16x32_bf16 v[154:157], v[0:3], v[100:103], v[88:91]
	s_barrier
	s_nop 1
	ds_read_b128 v[88:91], v204 offset:11008
	ds_read_b128 v[150:153], v204 offset:13056
	v_mfma_f32_16x16x32_bf16 v[102:105], v[76:79], v[126:129], v[92:95]
	ds_read_b128 v[142:145], v205 offset:11008
	s_nop 1
	ds_read_b128 v[92:95], v205 offset:13056
	ds_read_b64 v[76:77], v206 offset:15104
	ds_read_b128 v[138:141], v207 offset:15616
	v_mfma_f32_16x16x32_bf16 v[102:105], v[72:75], v[130:133], v[102:105]
	ds_read_b128 v[130:133], v207 offset:15872
	ds_read_b128 v[122:125], v207 offset:16128
	ds_read_b128 v[134:137], v208 offset:21824
	ds_read_b128 v[126:129], v208 offset:21888
	v_mfma_f32_16x16x32_bf16 v[72:75], v[72:75], v[146:149], v[102:105]
	s_nop 2
	ds_read_b128 v[100:103], v208 offset:21760
	ds_read_b128 v[118:121], v207 offset:16384
	s_nop 2
	v_cvt_pk_bf16_f32 v158, -v72, -v73
	v_cvt_pk_bf16_f32 v159, -v74, -v75
	v_lshlrev_b32_e32 v0, 16, v158
	v_and_b32_e32 v1, 0xffff0000, v158
	v_sub_f32_e64 v0, -v72, v0
	v_sub_f32_e64 v1, -v73, v1
	v_mfma_f32_16x16x32_bf16 v[96:99], v[60:63], v[158:161], v[96:99]
	v_cvt_pk_bf16_f32 v0, v0, v1
	v_lshlrev_b32_e32 v1, 16, v159
	v_and_b32_e32 v2, 0xffff0000, v159
	v_sub_f32_e64 v1, -v74, v1
	v_sub_f32_e64 v2, -v75, v2
	v_cvt_pk_bf16_f32 v1, v1, v2
	v_mov_b32_e32 v2, v3
	s_nop 1
	v_mfma_f32_16x16x32_bf16 v[96:99], v[60:63], v[0:3], v[96:99]
	v_mul_f32_e64 v62, v116, v86
	v_mul_f32_e64 v63, v117, v87
	v_mul_f32_e32 v60, v114, v84
	v_mul_f32_e32 v61, v115, v85
	ds_read_b64 v[84:85], v209 offset:19712
	ds_read_b128 v[114:117], v208 offset:21952
	v_mfma_f32_16x16x32_bf16 v[60:63], v[56:59], v[158:161], v[60:63]
	v_mfma_f32_16x16x32_bf16 v[146:149], v[56:59], v[0:3], v[60:63]
	v_mul_f32_e64 v58, v112, v70
	v_mul_f32_e64 v59, v113, v71
	v_mul_f32_e32 v56, v110, v68
	v_mul_f32_e32 v57, v111, v69
	s_nop 3
	v_mfma_f32_16x16x32_bf16 v[56:59], v[52:55], v[158:161], v[56:59]
	s_nop 0
	v_mfma_f32_16x16x32_bf16 v[110:113], v[52:55], v[0:3], v[56:59]
	v_mul_f32_e64 v54, v108, v82
	v_mul_f32_e64 v55, v109, v83
	v_mul_f32_e32 v52, v106, v80
	v_mul_f32_e32 v53, v107, v81
	s_nop 0
	s_nop 0
	v_mfma_f32_16x16x32_bf16 v[52:55], v[64:67], v[158:161], v[52:55]
	global_store_dword v250, v154, s[24:25] offset:-4096
	v_mfma_f32_16x16x32_bf16 v[106:109], v[64:67], v[0:3], v[52:55]
	global_store_dword v250, v155, s[24:25] offset:-2048
	global_store_dword v250, v156, s[24:25]
	global_store_dword v250, v157, s[24:25] offset:2048
	v_add_u32_e32 v250, 0x8000, v250
	s_waitcnt vmcnt(19)
	ds_write_b128 v181, v[20:23]
	s_waitcnt vmcnt(18)
	ds_write_b128 v188, v[24:27]
	ds_write_b128 v189, v[28:31]
	s_cmpk_gt_u32 s34, 0xf9
	s_cbranch_scc1 .LBB0_929
	global_load_dwordx4 v[20:23], v248, s[100:101] offset:-4096
	s_nop 0
	global_load_dwordx4 v[24:27], v248, s[100:101]
	global_load_dwordx4 v[28:31], v249, s[100:101]

.LBB0_929:
	v_cvt_pk_bf16_f32 v52, v96, v97
	v_cvt_pk_bf16_f32 v53, v98, v99
	v_cvt_pk_bf16_f32 v54, v146, v147
	v_cvt_pk_bf16_f32 v55, v148, v149
	v_cvt_pk_bf16_f32 v60, v110, v111
	v_cvt_pk_bf16_f32 v61, v112, v113
	s_nop 0
	v_lshlrev_b32_e32 v0, 16, v52
	v_and_b32_e32 v1, 0xffff0000, v52
	v_sub_f32_e32 v0, v96, v0
	v_sub_f32_e32 v1, v97, v1
	v_cvt_pk_bf16_f32 v56, v0, v1
	v_lshlrev_b32_e32 v0, 16, v53
	v_and_b32_e32 v1, 0xffff0000, v53
	v_sub_f32_e32 v0, v98, v0
	v_sub_f32_e32 v1, v99, v1
	s_waitcnt lgkmcnt(14)
	v_mfma_f32_16x16x32_bf16 v[66:69], v[150:153], v[52:55], 0
	v_cvt_pk_bf16_f32 v57, v0, v1
	v_lshlrev_b32_e32 v0, 16, v54
	v_and_b32_e32 v1, 0xffff0000, v54
	v_sub_f32_e32 v0, v146, v0
	v_sub_f32_e32 v1, v147, v1
	v_cvt_pk_bf16_f32 v58, v0, v1
	v_lshlrev_b32_e32 v0, 16, v55
	v_and_b32_e32 v1, 0xffff0000, v55
	v_sub_f32_e32 v0, v148, v0
	v_sub_f32_e32 v1, v149, v1
	v_cvt_pk_bf16_f32 v59, v0, v1
	v_lshlrev_b32_e32 v0, 16, v60
	v_mfma_f32_16x16x32_bf16 v[68:71], v[150:153], v[56:59], v[66:69]
	v_and_b32_e32 v1, 0xffff0000, v60
	v_sub_f32_e32 v0, v110, v0
	v_sub_f32_e32 v1, v111, v1
	v_cvt_pk_bf16_f32 v64, v0, v1
	v_lshlrev_b32_e32 v0, 16, v61
	v_and_b32_e32 v1, 0xffff0000, v61
	v_cvt_pk_bf16_f32 v62, v106, v107
	v_cvt_pk_bf16_f32 v63, v108, v109
	v_sub_f32_e32 v0, v112, v0
	v_sub_f32_e32 v1, v113, v1
	s_waitcnt lgkmcnt(12)
	v_mfma_f32_16x16x32_bf16 v[68:71], v[92:95], v[60:63], v[68:71]
	v_cvt_pk_bf16_f32 v65, v0, v1
	v_lshlrev_b32_e32 v0, 16, v62
	v_and_b32_e32 v1, 0xffff0000, v62
	v_mfma_f32_16x16x32_bf16 v[52:55], v[88:91], v[52:55], 0
	v_sub_f32_e32 v0, v106, v0
	v_sub_f32_e32 v1, v107, v1
	v_cvt_pk_bf16_f32 v66, v0, v1
	v_lshlrev_b32_e32 v0, 16, v63
	v_and_b32_e32 v1, 0xffff0000, v63
	v_mov_b32_e32 v78, v3
	v_mov_b32_e32 v79, v3
	v_sub_f32_e32 v0, v108, v0
	v_sub_f32_e32 v1, v109, v1
	v_cvt_pk_bf16_f32 v67, v0, v1
	v_mfma_f32_16x16x32_bf16 v[52:55], v[88:91], v[56:59], v[52:55]
	v_mov_b32_e32 v86, v3
	v_mov_b32_e32 v87, v3
	v_mfma_f32_16x16x32_bf16 v[68:71], v[92:95], v[64:67], v[68:71]
	s_waitcnt lgkmcnt(6)
	v_mul_f32_e32 v112, v128, v112
	v_mul_f32_e32 v113, v129, v113
	v_mul_f32_e32 v110, v126, v110
	v_mul_f32_e32 v111, v127, v111
	s_waitcnt lgkmcnt(2)
	v_mul_f32_e32 v108, v116, v108
	v_mul_f32_e32 v109, v117, v109
	v_mfma_f32_16x16x32_bf16 v[156:159], v[76:79], v[84:87], v[68:71]
	v_mul_f32_e64 v106, v114, v106
	v_mul_f32_e64 v107, v115, v107
	s_waitcnt lgkmcnt(0)
	s_barrier
	v_mfma_f32_16x16x32_bf16 v[68:71], v[142:145], v[60:63], v[52:55]
	ds_read_b128 v[76:79], v204
	ds_read_b128 v[92:95], v204 offset:2048
	ds_read_b128 v[72:75], v205
	ds_read_b128 v[88:91], v205 offset:2048
	ds_read_b64 v[104:105], v206 offset:4096
	ds_read_b128 v[60:63], v207 offset:4608
	ds_read_b128 v[56:59], v207 offset:4864
	ds_read_b128 v[52:55], v207 offset:5120
	v_mfma_f32_16x16x32_bf16 v[64:67], v[142:145], v[64:67], v[68:71]
	v_mov_b32_e32 v144, v84
	v_mov_b32_e32 v145, v85
	s_nop 0
	v_mul_f32_e32 v70, v102, v98
	v_mul_f32_e32 v71, v103, v99
	v_mul_f32_e32 v68, v100, v96
	v_mul_f32_e32 v69, v101, v97
	s_nop 2
	v_cvt_pk_bf16_f32 v142, -v64, -v65
	v_cvt_pk_bf16_f32 v143, -v66, -v67
	v_lshlrev_b32_e32 v0, 16, v142
	v_and_b32_e32 v1, 0xffff0000, v142
	v_sub_f32_e64 v0, -v64, v0
	v_sub_f32_e64 v1, -v65, v1
	v_mfma_f32_16x16x32_bf16 v[68:71], v[138:141], v[142:145], v[68:71]
	v_cvt_pk_bf16_f32 v0, v0, v1
	v_lshlrev_b32_e32 v1, 16, v143
	v_and_b32_e32 v2, 0xffff0000, v143
	v_sub_f32_e64 v1, -v66, v1
	v_sub_f32_e64 v2, -v67, v2
	v_mul_f32_e32 v66, v136, v148
	v_mul_f32_e32 v67, v137, v149
	v_mul_f32_e32 v64, v134, v146
	v_mul_f32_e32 v65, v135, v147
	v_cvt_pk_bf16_f32 v1, v1, v2
	v_mov_b32_e32 v2, v3
	v_mfma_f32_16x16x32_bf16 v[134:137], v[130:133], v[142:145], v[64:67]
	s_nop 0
	v_mfma_f32_16x16x32_bf16 v[110:113], v[122:125], v[142:145], v[110:113]
	v_mfma_f32_16x16x32_bf16 v[106:109], v[118:121], v[142:145], v[106:109]
	s_nop 0
	v_mfma_f32_16x16x32_bf16 v[138:141], v[138:141], v[0:3], v[68:71]
	ds_read_b128 v[84:87], v208 offset:10816
	s_nop 1
	ds_read_b128 v[68:71], v208 offset:10880
	ds_read_b128 v[96:99], v208 offset:10752
	ds_read_b128 v[64:67], v207 offset:5376
	ds_read_b64 v[100:101], v209 offset:8704
	ds_read_b128 v[80:83], v208 offset:10944
	global_store_dword v250, v156, s[24:25] offset:-4096
	v_mfma_f32_16x16x32_bf16 v[146:149], v[130:133], v[0:3], v[134:137]
	global_store_dword v250, v157, s[24:25] offset:-2048
	global_store_dword v250, v158, s[24:25]
	global_store_dword v250, v159, s[24:25] offset:2048
	v_add_u32_e32 v250, 0x8000, v250
	s_waitcnt vmcnt(17)
	ds_write_b128 v181, v[32:35] offset:11008
	s_waitcnt vmcnt(16)
	ds_write_b128 v188, v[36:39] offset:11008
	v_mfma_f32_16x16x32_bf16 v[152:155], v[122:125], v[0:3], v[110:113]
	v_mfma_f32_16x16x32_bf16 v[158:161], v[118:121], v[0:3], v[106:109]
	ds_write_b128 v189, v[40:43] offset:11008
	s_cmpk_gt_u32 s34, 0xf8
	s_cbranch_scc1 .LBB0_935
	global_load_dwordx4 v[32:35], v248, s[100:101] offset:-4096
	s_nop 0
	global_load_dwordx4 v[36:39], v248, s[100:101]
	global_load_dwordx4 v[40:43], v249, s[100:101]

.LBB0_935:
	v_cvt_pk_bf16_f32 v108, v138, v139
	v_cvt_pk_bf16_f32 v109, v140, v141
	v_cvt_pk_bf16_f32 v110, v146, v147
	v_cvt_pk_bf16_f32 v111, v148, v149
	v_cvt_pk_bf16_f32 v122, v152, v153
	v_cvt_pk_bf16_f32 v123, v154, v155
	s_nop 0
	v_lshlrev_b32_e32 v0, 16, v108
	v_and_b32_e32 v1, 0xffff0000, v108
	v_sub_f32_e32 v0, v138, v0
	v_sub_f32_e32 v1, v139, v1
	v_cvt_pk_bf16_f32 v112, v0, v1
	v_lshlrev_b32_e32 v0, 16, v109
	v_and_b32_e32 v1, 0xffff0000, v109
	v_sub_f32_e32 v0, v140, v0
	v_sub_f32_e32 v1, v141, v1
	s_waitcnt lgkmcnt(14)
	v_mfma_f32_16x16x32_bf16 v[116:119], v[92:95], v[108:111], 0
	v_cvt_pk_bf16_f32 v113, v0, v1
	v_lshlrev_b32_e32 v0, 16, v110
	v_and_b32_e32 v1, 0xffff0000, v110
	v_sub_f32_e32 v0, v146, v0
	v_sub_f32_e32 v1, v147, v1
	v_cvt_pk_bf16_f32 v114, v0, v1
	v_lshlrev_b32_e32 v0, 16, v111
	v_and_b32_e32 v1, 0xffff0000, v111
	v_sub_f32_e32 v0, v148, v0
	v_sub_f32_e32 v1, v149, v1
	v_cvt_pk_bf16_f32 v115, v0, v1
	v_lshlrev_b32_e32 v0, 16, v122
	v_mfma_f32_16x16x32_bf16 v[116:119], v[92:95], v[112:115], v[116:119]
	v_and_b32_e32 v1, 0xffff0000, v122
	v_sub_f32_e32 v0, v152, v0
	v_sub_f32_e32 v1, v153, v1
	v_cvt_pk_bf16_f32 v126, v0, v1
	v_lshlrev_b32_e32 v0, 16, v123
	v_and_b32_e32 v1, 0xffff0000, v123
	v_cvt_pk_bf16_f32 v124, v158, v159
	v_cvt_pk_bf16_f32 v125, v160, v161
	v_sub_f32_e32 v0, v154, v0
	v_sub_f32_e32 v1, v155, v1
	s_waitcnt lgkmcnt(12)
	v_mfma_f32_16x16x32_bf16 v[116:119], v[88:91], v[122:125], v[116:119]
	v_cvt_pk_bf16_f32 v127, v0, v1
	v_lshlrev_b32_e32 v0, 16, v124
	v_and_b32_e32 v1, 0xffff0000, v124
	v_sub_f32_e32 v0, v158, v0
	v_sub_f32_e32 v1, v159, v1
	v_cvt_pk_bf16_f32 v128, v0, v1
	v_lshlrev_b32_e32 v0, 16, v125
	v_and_b32_e32 v1, 0xffff0000, v125
	v_mov_b32_e32 v106, v3
	v_mov_b32_e32 v107, v3
	v_sub_f32_e32 v0, v160, v0
	v_sub_f32_e32 v1, v161, v1
	v_cvt_pk_bf16_f32 v129, v0, v1
	v_mov_b32_e32 v102, v3
	v_mfma_f32_16x16x32_bf16 v[116:119], v[88:91], v[126:129], v[116:119]
	v_mov_b32_e32 v103, v3
	s_waitcnt lgkmcnt(3)
	v_mov_b32_e32 v216, v100
	v_mov_b32_e32 v217, v101
	v_mfma_f32_16x16x32_bf16 v[210:213], v[104:107], v[100:103], v[116:119]
	v_mul_f32_e64 v154, v70, v154
	v_mul_f32_e64 v155, v71, v155
	v_mul_f32_e32 v152, v68, v152
	v_mul_f32_e32 v153, v69, v153
	s_waitcnt lgkmcnt(2)
	v_mul_f32_e32 v160, v82, v160
	v_mul_f32_e32 v161, v83, v161
	v_mfma_f32_16x16x32_bf16 v[106:109], v[76:79], v[108:111], 0
	v_mul_f32_e64 v158, v80, v158
	v_mul_f32_e64 v159, v81, v159
	s_waitcnt lgkmcnt(0)
	s_barrier
	v_mfma_f32_16x16x32_bf16 v[106:109], v[76:79], v[112:115], v[106:109]
	ds_read_b128 v[118:121], v204 offset:11008
	ds_read_b128 v[170:173], v204 offset:13056
	ds_read_b128 v[134:137], v205 offset:11008
	ds_read_b128 v[162:165], v205 offset:13056
	v_mfma_f32_16x16x32_bf16 v[122:125], v[72:75], v[122:125], v[106:109]
	ds_read_b64 v[150:151], v206 offset:15104
	ds_read_b128 v[114:117], v207 offset:15616
	ds_read_b128 v[110:113], v207 offset:15872
	ds_read_b128 v[106:109], v207 offset:16128
	v_mfma_f32_16x16x32_bf16 v[122:125], v[72:75], v[126:129], v[122:125]
	v_mul_f32_e64 v128, v98, v140
	v_mul_f32_e64 v129, v99, v141
	v_mul_f32_e32 v126, v96, v138
	v_mul_f32_e32 v127, v97, v139
	ds_read_b128 v[138:141], v208 offset:21824
	ds_read_b128 v[130:133], v208 offset:21888
	s_nop 1
	s_nop 0
	v_cvt_pk_bf16_f32 v214, -v122, -v123
	v_cvt_pk_bf16_f32 v215, -v124, -v125
	v_lshlrev_b32_e32 v0, 16, v214
	v_and_b32_e32 v1, 0xffff0000, v214
	v_sub_f32_e64 v0, -v122, v0
	v_sub_f32_e64 v1, -v123, v1
	v_mfma_f32_16x16x32_bf16 v[126:129], v[60:63], v[214:217], v[126:129]
	v_cvt_pk_bf16_f32 v0, v0, v1
	v_lshlrev_b32_e32 v1, 16, v215
	v_and_b32_e32 v2, 0xffff0000, v215
	v_sub_f32_e64 v1, -v124, v1
	v_sub_f32_e64 v2, -v125, v2
	v_mul_f32_e32 v124, v86, v148
	v_mul_f32_e32 v125, v87, v149
	v_mul_f32_e32 v122, v84, v146
	v_mul_f32_e32 v123, v85, v147
	v_cvt_pk_bf16_f32 v1, v1, v2
	v_mov_b32_e32 v2, v3
	v_mfma_f32_16x16x32_bf16 v[152:155], v[52:55], v[214:217], v[152:155]
	s_cmpk_lt_u32 s34, 0xfc
	v_mfma_f32_16x16x32_bf16 v[146:149], v[56:59], v[214:217], v[122:125]
	s_cselect_b64 s[12:13], -1, 0
	s_cmpk_gt_u32 s34, 0xfb
	v_mfma_f32_16x16x32_bf16 v[158:161], v[64:67], v[214:217], v[158:161]
	s_cselect_b64 s[40:41], -1, 0
	s_and_b64 vcc, exec, s[40:41]
	v_mfma_f32_16x16x32_bf16 v[142:145], v[60:63], v[0:3], v[126:129]
	ds_read_b128 v[166:169], v208 offset:21760
	ds_read_b128 v[122:125], v207 offset:16384
	ds_read_b64 v[174:175], v209 offset:19712
	ds_read_b128 v[126:129], v208 offset:21952
	global_store_dword v250, v210, s[24:25] offset:-4096
	global_store_dword v250, v211, s[24:25] offset:-2048
	global_store_dword v250, v212, s[24:25]
	global_store_dword v250, v213, s[24:25] offset:2048
	v_add_u32_e32 v250, 0x8000, v250
	v_mfma_f32_16x16x32_bf16 v[146:149], v[56:59], v[0:3], v[146:149]
	v_mfma_f32_16x16x32_bf16 v[154:157], v[52:55], v[0:3], v[152:155]
	v_mfma_f32_16x16x32_bf16 v[158:161], v[64:67], v[0:3], v[158:161]
	s_cbranch_vccnz .LBB0_939
	s_waitcnt vmcnt(23)
	ds_write_b128 v181, v[44:47]
	s_waitcnt vmcnt(22)
	ds_write_b128 v188, v[48:51]
	ds_write_b128 v189, v[4:7]
.LBB0_939:
	s_cmpk_gt_u32 s34, 0xf7
	s_cbranch_scc1 .LBB0_943
	s_waitcnt vmcnt(22)
	global_load_dwordx4 v[44:47], v248, s[100:101] offset:-4096
	s_nop 0
	global_load_dwordx4 v[48:51], v248, s[100:101]
	global_load_dwordx4 v[4:7], v249, s[100:101]
